# v083 + NA loop-carried P fragment kept in v[118:121] (per-row copies through v[122:125] removed)
# speedup vs baseline: 1.0021x; 1.0021x over previous
.Lna_nodma:
	s_cmp_lt_u32 s76, s81
	s_cselect_b64 s[74:75], -1, 0
	s_cmp_gt_u32 s76, s3
	s_cselect_b64 s[76:77], -1, 0
	s_or_b64 s[74:75], s[74:75], s[76:77]
	s_and_b64 vcc, exec, s[74:75]
	s_cbranch_vccnz .LBB0_249
	s_mul_hi_u32 s11, s10, 0x24924925
	s_sub_i32 s74, s10, s11
	s_lshr_b32 s74, s74, 1
	s_add_i32 s74, s74, s11
	s_lshr_b32 s11, s74, 2
	s_mul_i32 s11, s11, 0x1c000
	s_sub_i32 s11, s78, s11
	s_add_i32 s11, s11, 0
	v_add_u32_e32 v130, s11, v158
	v_add_u32_e32 v70, v130, v154
	v_add_u32_e32 v126, v130, v159
	ds_read_b128 v[174:177], v70
	ds_read_b128 v[178:181], v70 offset:4096
	v_add_u32_e32 v131, v130, v160
	ds_read_b128 v[182:185], v126
	ds_read_b128 v[186:189], v126 offset:4096
	v_add_u32_e32 v130, v130, v161
	ds_read_b128 v[190:193], v131
	ds_read_b128 v[194:197], v131 offset:4096
	ds_read_b128 v[198:201], v130
	ds_read_b128 v[202:205], v130 offset:4096
	v_readlane_b32 s76, v252, 32
	v_readlane_b32 s77, v252, 33
	v_add_u32_e32 v165, 0x205f0, v147
	s_mov_b64 s[74:75], -1
	s_and_b64 vcc, exec, s[76:77]
	s_waitcnt lgkmcnt(7)
	v_mfma_f32_32x32x16_bf16 v[82:97], v[174:177], v[98:101], v[32:47]
	s_waitcnt lgkmcnt(6)
	v_mfma_f32_32x32x16_bf16 v[66:81], v[178:181], v[98:101], v[48:63]
	s_waitcnt lgkmcnt(5)
	v_mfma_f32_32x32x16_bf16 v[82:97], v[182:185], v[102:105], v[82:97]
	s_waitcnt lgkmcnt(4)
	v_mfma_f32_32x32x16_bf16 v[66:81], v[186:189], v[102:105], v[66:81]
	s_waitcnt lgkmcnt(3)
	v_mfma_f32_32x32x16_bf16 v[82:97], v[190:193], v[106:109], v[82:97]
	s_waitcnt lgkmcnt(2)
	v_mfma_f32_32x32x16_bf16 v[66:81], v[194:197], v[106:109], v[66:81]
	s_waitcnt lgkmcnt(1)
	v_mfma_f32_32x32x16_bf16 v[82:97], v[198:201], v[110:113], v[82:97]
	s_waitcnt lgkmcnt(0)
	v_mfma_f32_32x32x16_bf16 v[66:81], v[202:205], v[110:113], v[66:81]
	s_cbranch_vccz .LBB0_238
	ds_read2_b32 v[122:123], v165 offset0:40 offset1:41
	ds_read2_b32 v[124:125], v165 offset0:42 offset1:43
	ds_read2_b32 v[126:127], v165 offset0:48 offset1:49
	ds_read2_b32 v[128:129], v165 offset0:50 offset1:51
	ds_read2_b32 v[130:131], v165 offset0:32 offset1:33
	ds_read2_b32 v[132:133], v165 offset0:56 offset1:57
	ds_read2_b32 v[134:135], v165 offset0:34 offset1:35
	ds_read2_b32 v[136:137], v165 offset0:58 offset1:59
	ds_read2_b32 v[170:171], v165 offset0:24 offset1:25
	ds_read2_b32 v[172:173], v165 offset0:26 offset1:27
	s_mov_b64 s[74:75], 0
	s_waitcnt lgkmcnt(1)
	v_mov_b32_e32 v163, v170
	s_waitcnt lgkmcnt(0)
	v_mov_b32_e32 v169, v172
	s_nop 0
	v_pk_add_f32 v[130:131], v[66:67], v[130:131]
	v_exp_f32_e32 v130, v130
	v_exp_f32_e32 v131, v131
	v_pk_add_f32 v[134:135], v[68:69], v[134:135]
	v_exp_f32_e32 v134, v134
	v_exp_f32_e32 v135, v135
	v_pk_add_f32 v[70:71], v[70:71], v[122:123]
	v_exp_f32_e32 v70, v70
	v_add_f32_e32 v170, v131, v130
	v_exp_f32_e32 v71, v71
	v_pk_add_f32 v[72:73], v[72:73], v[124:125]
	v_add_f32_e32 v170, v134, v170
	v_exp_f32_e32 v72, v72
	v_add_f32_e32 v170, v135, v170
	v_exp_f32_e32 v73, v73
	v_pk_add_f32 v[74:75], v[74:75], v[126:127]
	v_add_f32_e32 v122, v70, v170
	v_exp_f32_e32 v74, v74
	v_add_f32_e32 v122, v71, v122
	v_exp_f32_e32 v75, v75
	v_pk_add_f32 v[76:77], v[76:77], v[128:129]
	v_add_f32_e32 v122, v72, v122
	v_exp_f32_e32 v76, v76
	v_add_f32_e32 v122, v73, v122
	v_exp_f32_e32 v77, v77
	v_pk_add_f32 v[78:79], v[78:79], v[132:133]
	v_add_f32_e32 v122, v74, v122
	v_exp_f32_e32 v78, v78
	v_add_f32_e32 v122, v75, v122
	v_exp_f32_e32 v79, v79
	v_pk_add_f32 v[80:81], v[80:81], v[136:137]
	v_add_f32_e32 v122, v76, v122
	v_exp_f32_e32 v80, v80
	v_add_f32_e32 v122, v77, v122
	v_exp_f32_e32 v81, v81
	v_add_f32_e32 v123, v94, v163
	v_add_f32_e32 v122, v78, v122
	v_exp_f32_e32 v123, v123
	v_add_f32_e32 v124, v95, v171
	v_add_f32_e32 v122, v79, v122
	v_exp_f32_e32 v124, v124
	v_add_f32_e32 v125, v96, v169
	v_add_f32_e32 v126, v97, v173
	v_add_f32_e32 v122, v80, v122
	v_exp_f32_e32 v125, v125
	v_exp_f32_e32 v126, v126
	v_add_f32_e32 v122, v81, v122
	v_add_f32_e32 v122, v123, v122
	v_add_f32_e32 v122, v124, v122
	v_add_f32_e32 v122, v125, v122
	v_cvt_pk_bf16_f32 v132, v123, v124
	v_cvt_pk_bf16_f32 v133, v125, v126
	v_cvt_pk_bf16_f32 v120, v78, v79
	v_cvt_pk_bf16_f32 v121, v80, v81
	v_add_f32_e32 v163, v126, v122
	v_cvt_pk_bf16_f32 v127, v134, v135
	v_cvt_pk_bf16_f32 v118, v74, v75
	v_cvt_pk_bf16_f32 v119, v76, v77
	v_mov_b64_e32 v[136:137], v[120:121]
	v_cvt_pk_bf16_f32 v126, v130, v131
	v_cvt_pk_bf16_f32 v128, v70, v71
	v_cvt_pk_bf16_f32 v129, v72, v73
	v_mov_b64_e32 v[134:135], v[118:119]
.LBB0_238:
	v_mov_b32_e32 v130, 0
	s_andn2_b64 vcc, exec, s[74:75]
	v_mov_b32_e32 v131, v130
	s_cbranch_vccnz .LBB0_240
	s_nop 6
	ds_read2_b32 v[114:115], v165 offset0:26 offset1:27
	ds_read2_b32 v[116:117], v165 offset0:18 offset1:19
	ds_read2_b32 v[122:123], v165 offset0:32 offset1:33
	ds_read2_b32 v[124:125], v165 offset0:34 offset1:35
	ds_read2_b32 v[70:71], v165 offset1:1
	ds_read2_b32 v[72:73], v165 offset0:2 offset1:3
	ds_read2_b32 v[74:75], v165 offset0:8 offset1:9
	ds_read2_b32 v[76:77], v165 offset0:10 offset1:11
	ds_read2_b32 v[78:79], v165 offset0:16 offset1:17
	ds_read2_b32 v[80:81], v165 offset0:24 offset1:25
	s_waitcnt lgkmcnt(0)
	s_nop 0
	v_pk_add_f32 v[70:71], v[82:83], v[70:71]
	v_exp_f32_e32 v70, v70
	v_exp_f32_e32 v71, v71
	v_pk_add_f32 v[72:73], v[84:85], v[72:73]
	v_exp_f32_e32 v72, v72
	v_exp_f32_e32 v73, v73
	v_pk_add_f32 v[74:75], v[86:87], v[74:75]
	v_exp_f32_e32 v74, v74
	v_add_f32_e32 v82, v71, v70
	v_exp_f32_e32 v75, v75
	v_pk_add_f32 v[76:77], v[88:89], v[76:77]
	v_add_f32_e32 v82, v72, v82
	v_exp_f32_e32 v76, v76
	v_add_f32_e32 v82, v73, v82
	v_exp_f32_e32 v77, v77
	v_pk_add_f32 v[78:79], v[90:91], v[78:79]
	v_add_f32_e32 v82, v74, v82
	v_exp_f32_e32 v78, v78
	v_add_f32_e32 v82, v75, v82
	v_exp_f32_e32 v79, v79
	v_add_f32_e32 v83, v92, v116
	v_add_f32_e32 v82, v76, v82
	v_exp_f32_e32 v83, v83
	v_add_f32_e32 v84, v93, v117
	v_add_f32_e32 v82, v77, v82
	v_exp_f32_e32 v84, v84
	v_pk_add_f32 v[80:81], v[94:95], v[80:81]
	v_add_f32_e32 v82, v78, v82
	v_exp_f32_e32 v80, v80
	v_add_f32_e32 v82, v79, v82
	v_exp_f32_e32 v81, v81
	v_add_f32_e32 v85, v96, v114
	v_add_f32_e32 v82, v83, v82
	v_exp_f32_e32 v85, v85
	v_add_f32_e32 v86, v97, v115
	v_add_f32_e32 v82, v84, v82
	v_exp_f32_e32 v86, v86
	v_pk_add_f32 v[66:67], v[66:67], v[122:123]
	v_add_f32_e32 v82, v80, v82
	v_exp_f32_e32 v66, v66
	v_add_f32_e32 v82, v81, v82
	v_exp_f32_e32 v67, v67
	v_pk_add_f32 v[68:69], v[68:69], v[124:125]
	v_add_f32_e32 v82, v85, v82
	v_exp_f32_e32 v68, v68
	v_add_f32_e32 v82, v86, v82
	v_exp_f32_e32 v69, v69
	v_add_f32_e32 v82, v66, v82
	v_add_f32_e32 v82, v67, v82
	v_add_f32_e32 v82, v68, v82
	v_mov_b64_e32 v[136:137], v[120:121]
	v_add_f32_e32 v163, v69, v82
	v_cvt_pk_bf16_f32 v114, v70, v71
	v_cvt_pk_bf16_f32 v115, v72, v73
	v_cvt_pk_bf16_f32 v116, v74, v75
	v_cvt_pk_bf16_f32 v117, v76, v77
	v_cvt_pk_bf16_f32 v130, v78, v79
	v_cvt_pk_bf16_f32 v131, v83, v84
	v_cvt_pk_bf16_f32 v132, v80, v81
	v_cvt_pk_bf16_f32 v133, v85, v86
	v_cvt_pk_bf16_f32 v126, v66, v67
	v_cvt_pk_bf16_f32 v127, v68, v69
	v_mov_b32_e32 v128, 0
	v_mov_b64_e32 v[134:135], v[118:119]
	v_mov_b32_e32 v129, 0

.LBB0_249:
.LBB0_250:
	s_add_i32 s10, s10, 1
	s_add_i32 s87, s87, 1
	s_addk_i32 s78, 0x4000
	s_addk_i32 s9, 0x4000
	s_add_i32 s8, s8, 1
	s_cmp_lg_u32 s7, s87
	v_add_u32_e32 v147, 0x7c, v147
	s_cbranch_scc0 .LBB0_252
	s_branch .LBB0_235
